# strategy 9 (7.12) continued: row-sum copy for the cross-half swap taken right after the last add into a spare VGPR, rescale test moved into the exp wait state; two s_nop per step removed from the seri
# baseline (speedup 1.0000x reference)
.LBB0_563:
	s_add_i32 s13, s12, -1
	s_min_u32 s34, s13, s4
	s_lshl_b64 s[30:31], s[34:35], 13
	v_lshl_add_u64 v[2:3], v[224:225], 0, s[30:31]
	global_load_dwordx4 v[196:199], v[2:3], off
	v_add_co_u32_e32 v2, vcc, s1, v218
	ds_read_b128 v[6:9], v243
	ds_read_b128 v[12:15], v242 offset:59392
	v_addc_co_u32_e32 v3, vcc, -1, v219, vcc
	global_load_dwordx4 v[200:203], v[2:3], off offset:-4096
	global_load_dwordx4 v[204:207], v[2:3], off
	ds_read_b128 v[2:5], v243 offset:4608
	s_waitcnt lgkmcnt(0)
	v_mfma_f32_32x32x16_bf16 v[160:175], v[6:9], v[12:15], v[96:111]
	ds_read_b128 v[112:115], v243 offset:32
	v_exp_f32_e32 v0, v128
	v_exp_f32_e32 v6, v129
	ds_read_b128 v[116:119], v242 offset:60416
	v_add_f32_e32 v11, v6, v0
	v_cvt_pk_bf16_f32 v10, v0, v6
	v_mfma_f32_32x32x16_bf16 v[144:159], v[2:5], v[12:15], v[96:111]
	ds_read_b128 v[6:9], v243 offset:4640
	v_exp_f32_e32 v0, v130
	v_exp_f32_e32 v120, v131
	v_add_f32_e32 v121, v0, v11
	v_cvt_pk_bf16_f32 v11, v0, v120
	v_add_f32_e32 v0, v120, v121
	s_waitcnt lgkmcnt(1)
	v_mfma_f32_32x32x16_bf16 v[160:175], v[112:115], v[116:119], v[160:175]
	ds_read_b128 v[2:5], v243 offset:64
	ds_read_b128 v[120:123], v242 offset:61440
	v_exp_f32_e32 v12, v132
	v_exp_f32_e32 v13, v133
	v_add_f32_e32 v0, v12, v0
	v_add_f32_e32 v0, v13, v0
	v_cvt_pk_bf16_f32 v12, v12, v13
	s_waitcnt lgkmcnt(2)
	v_mfma_f32_32x32x16_bf16 v[144:159], v[6:9], v[116:119], v[144:159]
	ds_read_b128 v[112:115], v243 offset:4672
	v_exp_f32_e32 v6, v134
	v_exp_f32_e32 v7, v135
	v_add_f32_e32 v0, v6, v0
	v_add_f32_e32 v0, v7, v0
	v_cvt_pk_bf16_f32 v13, v6, v7
	s_waitcnt lgkmcnt(1)
	v_mfma_f32_32x32x16_bf16 v[160:175], v[2:5], v[120:123], v[160:175]
	ds_read_b128 v[116:119], v243 offset:96
	ds_read_b128 v[124:127], v242 offset:62464
	v_exp_f32_e32 v2, v136
	v_exp_f32_e32 v3, v137
	v_add_f32_e32 v0, v2, v0
	v_add_f32_e32 v0, v3, v0
	v_cvt_pk_bf16_f32 v6, v2, v3
	s_waitcnt lgkmcnt(2)
	v_mfma_f32_32x32x16_bf16 v[144:159], v[112:115], v[120:123], v[144:159]
	ds_read_b128 v[2:5], v243 offset:4704
	v_exp_f32_e32 v7, v138
	v_exp_f32_e32 v8, v139
	v_add_f32_e32 v0, v7, v0
	v_add_f32_e32 v0, v8, v0
	v_cvt_pk_bf16_f32 v7, v7, v8
	s_waitcnt lgkmcnt(1)
	v_mfma_f32_32x32x16_bf16 v[160:175], v[116:119], v[124:127], v[160:175]
	ds_read_b64_tr_b16 v[112:113], v244 offset:18432
	ds_read_b64_tr_b16 v[114:115], v244 offset:20992
	v_exp_f32_e32 v8, v140
	v_exp_f32_e32 v9, v141
	v_add_f32_e32 v0, v8, v0
	v_add_f32_e32 v0, v9, v0
	v_cvt_pk_bf16_f32 v8, v8, v9
	s_waitcnt lgkmcnt(2)
	v_mfma_f32_32x32x16_bf16 v[144:159], v[2:5], v[124:127], v[144:159]
	ds_read_b64_tr_b16 v[116:117], v244 offset:18496
	ds_read_b64_tr_b16 v[118:119], v244 offset:21056
	v_exp_f32_e32 v9, v142
	v_exp_f32_e32 v14, v143
	v_add_f32_e32 v0, v9, v0
	v_add_f32_e32 v0, v14, v0
	v_cvt_pk_bf16_f32 v9, v9, v14
	s_waitcnt lgkmcnt(2)
	v_mfma_f32_32x32x16_bf16 v[64:79], v[112:115], v[188:191], v[64:79]
	ds_read_b64_tr_b16 v[120:121], v244 offset:18560
	ds_read_b64_tr_b16 v[122:123], v244 offset:21120
	v_exp_f32_e32 v2, v80
	v_max3_f32 v3, v160, s33, v144
	v_add_f32_e32 v0, v2, v0
	s_waitcnt lgkmcnt(2)
	v_mfma_f32_32x32x16_bf16 v[48:63], v[116:119], v[188:191], v[48:63]
	ds_read_b64_tr_b16 v[112:113], v244 offset:18624
	ds_read_b64_tr_b16 v[114:115], v244 offset:21184
	v_exp_f32_e32 v4, v81
	v_max3_f32 v3, v3, v161, v145
	v_add_f32_e32 v0, v4, v0
	v_cvt_pk_bf16_f32 v2, v2, v4
	s_waitcnt lgkmcnt(2)
	v_mfma_f32_32x32x16_bf16 v[32:47], v[120:123], v[188:191], v[32:47]
	ds_read_b64_tr_b16 v[116:117], v244 offset:23552
	ds_read_b64_tr_b16 v[118:119], v244 offset:26112
	v_exp_f32_e32 v4, v82
	v_max3_f32 v5, v3, v162, v146
	v_add_f32_e32 v0, v4, v0
	s_waitcnt lgkmcnt(2)
	v_mfma_f32_32x32x16_bf16 v[16:31], v[112:115], v[188:191], v[16:31]
	ds_read_b64_tr_b16 v[120:121], v244 offset:23616
	v_exp_f32_e32 v3, v83
	ds_read_b64_tr_b16 v[122:123], v244 offset:26176
	v_add_f32_e32 v0, v3, v0
	v_cvt_pk_bf16_f32 v3, v4, v3
	v_max3_f32 v4, v5, v163, v147
	s_waitcnt lgkmcnt(2)
	v_mfma_f32_32x32x16_bf16 v[64:79], v[116:119], v[184:187], v[64:79]
	ds_read_b64_tr_b16 v[80:81], v244 offset:23680
	ds_read_b64_tr_b16 v[82:83], v244 offset:26240
	v_exp_f32_e32 v5, v84
	v_max3_f32 v14, v4, v164, v148
	v_add_f32_e32 v0, v5, v0
	s_waitcnt lgkmcnt(2)
	v_mfma_f32_32x32x16_bf16 v[48:63], v[120:123], v[184:187], v[48:63]
	ds_read_b64_tr_b16 v[112:113], v244 offset:23744
	v_exp_f32_e32 v4, v85
	ds_read_b64_tr_b16 v[114:115], v244 offset:26304
	v_add_f32_e32 v0, v4, v0
	v_cvt_pk_bf16_f32 v4, v5, v4
	v_max3_f32 v5, v14, v165, v149
	s_waitcnt lgkmcnt(2)
	v_mfma_f32_32x32x16_bf16 v[32:47], v[80:83], v[184:187], v[32:47]
	ds_read_b64_tr_b16 v[116:117], v244 offset:28672
	ds_read_b64_tr_b16 v[118:119], v244 offset:31232
	v_exp_f32_e32 v14, v86
	v_max3_f32 v15, v5, v166, v150
	v_add_f32_e32 v0, v14, v0
	s_waitcnt lgkmcnt(2)
	v_mfma_f32_32x32x16_bf16 v[16:31], v[112:115], v[184:187], v[16:31]
	ds_read_b64_tr_b16 v[80:81], v244 offset:28736
	v_exp_f32_e32 v5, v87
	ds_read_b64_tr_b16 v[82:83], v244 offset:31296
	v_add_f32_e32 v0, v5, v0
	v_cvt_pk_bf16_f32 v5, v14, v5
	v_max3_f32 v14, v15, v167, v151
	s_waitcnt lgkmcnt(2)
	v_mfma_f32_32x32x16_bf16 v[64:79], v[116:119], v[176:179], v[64:79]
	ds_read_b64_tr_b16 v[84:85], v244 offset:28800
	ds_read_b64_tr_b16 v[86:87], v244 offset:31360
	v_exp_f32_e32 v15, v88
	v_max3_f32 v14, v14, v168, v152
	v_add_f32_e32 v0, v15, v0
	s_waitcnt lgkmcnt(2)
	v_mfma_f32_32x32x16_bf16 v[48:63], v[80:83], v[176:179], v[48:63]
	ds_read_b64_tr_b16 v[112:113], v244 offset:28864
	ds_read_b64_tr_b16 v[114:115], v244 offset:31424
	v_exp_f32_e32 v80, v89
	v_max3_f32 v14, v14, v169, v153
	v_add_f32_e32 v0, v80, v0
	v_cvt_pk_bf16_f32 v192, v15, v80
	s_waitcnt lgkmcnt(2)
	v_mfma_f32_32x32x16_bf16 v[32:47], v[84:87], v[176:179], v[32:47]
	ds_read_b64_tr_b16 v[80:81], v244 offset:33792
	ds_read_b64_tr_b16 v[82:83], v244 offset:36352
	v_exp_f32_e32 v15, v90
	v_max3_f32 v14, v14, v170, v154
	v_add_f32_e32 v0, v15, v0
	s_waitcnt lgkmcnt(2)
	v_mfma_f32_32x32x16_bf16 v[16:31], v[112:115], v[176:179], v[16:31]
	ds_read_b64_tr_b16 v[84:85], v244 offset:33856
	ds_read_b64_tr_b16 v[86:87], v244 offset:36416
	v_exp_f32_e32 v88, v91
	v_max3_f32 v14, v14, v171, v155
	v_add_f32_e32 v0, v88, v0
	v_cvt_pk_bf16_f32 v193, v15, v88
	s_waitcnt lgkmcnt(2)
	v_mfma_f32_32x32x16_bf16 v[64:79], v[80:83], v[180:183], v[64:79]
	ds_read_b64_tr_b16 v[88:89], v244 offset:33920
	ds_read_b64_tr_b16 v[90:91], v244 offset:36480
	v_exp_f32_e32 v15, v92
	v_max3_f32 v14, v14, v172, v156
	v_add_f32_e32 v0, v15, v0
	s_waitcnt lgkmcnt(2)
	v_mfma_f32_32x32x16_bf16 v[48:63], v[84:87], v[180:183], v[48:63]
	ds_read_b64_tr_b16 v[80:81], v244 offset:33984
	ds_read_b64_tr_b16 v[82:83], v244 offset:36544
	v_exp_f32_e32 v84, v93
	v_max3_f32 v14, v14, v173, v157
	v_add_f32_e32 v0, v84, v0
	v_cvt_pk_bf16_f32 v194, v15, v84
	s_waitcnt lgkmcnt(2)
	v_mfma_f32_32x32x16_bf16 v[32:47], v[88:91], v[180:183], v[32:47]
	v_exp_f32_e32 v15, v94
	v_max3_f32 v14, v14, v174, v158
	v_add_f32_e32 v0, v15, v0
	s_waitcnt lgkmcnt(0)
	v_mfma_f32_32x32x16_bf16 v[16:31], v[80:83], v[180:183], v[16:31]
	v_exp_f32_e32 v80, v95
	v_cmp_gt_f32_e32 vcc, 1.0, v226
	v_add_f32_e32 v0, v80, v0
	v_mov_b32_e32 v239, v0
	v_cvt_pk_bf16_f32 v195, v15, v80
	v_max3_f32 v15, v14, v175, v159
	v_permlane32_swap_b32_e32 v0, v239
	s_cbranch_vccz .LBB0_565
	v_pk_mul_f32 v[78:79], v[226:227], v[78:79] op_sel_hi:[0,1]
	v_pk_mul_f32 v[76:77], v[226:227], v[76:77] op_sel_hi:[0,1]
	v_pk_mul_f32 v[74:75], v[226:227], v[74:75] op_sel_hi:[0,1]
	v_pk_mul_f32 v[72:73], v[226:227], v[72:73] op_sel_hi:[0,1]
	v_pk_mul_f32 v[70:71], v[226:227], v[70:71] op_sel_hi:[0,1]
	v_pk_mul_f32 v[68:69], v[226:227], v[68:69] op_sel_hi:[0,1]
	v_pk_mul_f32 v[66:67], v[226:227], v[66:67] op_sel_hi:[0,1]
	v_pk_mul_f32 v[64:65], v[226:227], v[64:65] op_sel_hi:[0,1]
	v_pk_mul_f32 v[62:63], v[226:227], v[62:63] op_sel_hi:[0,1]
	v_pk_mul_f32 v[60:61], v[226:227], v[60:61] op_sel_hi:[0,1]
	v_pk_mul_f32 v[58:59], v[226:227], v[58:59] op_sel_hi:[0,1]
	v_pk_mul_f32 v[56:57], v[226:227], v[56:57] op_sel_hi:[0,1]
	v_pk_mul_f32 v[54:55], v[226:227], v[54:55] op_sel_hi:[0,1]
	v_pk_mul_f32 v[52:53], v[226:227], v[52:53] op_sel_hi:[0,1]
	v_pk_mul_f32 v[50:51], v[226:227], v[50:51] op_sel_hi:[0,1]
	v_pk_mul_f32 v[48:49], v[226:227], v[48:49] op_sel_hi:[0,1]
	v_pk_mul_f32 v[46:47], v[226:227], v[46:47] op_sel_hi:[0,1]
	v_pk_mul_f32 v[44:45], v[226:227], v[44:45] op_sel_hi:[0,1]
	v_pk_mul_f32 v[42:43], v[226:227], v[42:43] op_sel_hi:[0,1]
	v_pk_mul_f32 v[40:41], v[226:227], v[40:41] op_sel_hi:[0,1]
	v_pk_mul_f32 v[38:39], v[226:227], v[38:39] op_sel_hi:[0,1]
	v_pk_mul_f32 v[36:37], v[226:227], v[36:37] op_sel_hi:[0,1]
	v_pk_mul_f32 v[34:35], v[226:227], v[34:35] op_sel_hi:[0,1]
	v_pk_mul_f32 v[32:33], v[226:227], v[32:33] op_sel_hi:[0,1]
	v_pk_mul_f32 v[30:31], v[226:227], v[30:31] op_sel_hi:[0,1]
	v_pk_mul_f32 v[28:29], v[226:227], v[28:29] op_sel_hi:[0,1]
	v_pk_mul_f32 v[26:27], v[226:227], v[26:27] op_sel_hi:[0,1]
	v_pk_mul_f32 v[24:25], v[226:227], v[24:25] op_sel_hi:[0,1]
	v_pk_mul_f32 v[22:23], v[226:227], v[22:23] op_sel_hi:[0,1]
	v_pk_mul_f32 v[20:21], v[226:227], v[20:21] op_sel_hi:[0,1]
	v_pk_mul_f32 v[18:19], v[226:227], v[18:19] op_sel_hi:[0,1]
	v_pk_mul_f32 v[16:17], v[226:227], v[16:17] op_sel_hi:[0,1]
.LBB0_565:
	v_mov_b32_e32 v238, v15
	v_add_f32_e32 v0, v0, v239
	v_add_f32_e32 v14, v248, v0
	v_permlane32_swap_b32_e32 v15, v238
	v_max_f32_e32 v0, v238, v238
	v_max_f32_e32 v15, v15, v15
	v_max_f32_e32 v0, v15, v0
	v_cmp_lt_f32_e32 vcc, s28, v0
	s_cbranch_vccz .LBB0_567
	v_max_f32_e32 v0, v0, v0
	v_max_f32_e32 v80, 0, v0
	v_exp_f32_e64 v0, -v80
	v_add_f32_e32 v247, v247, v80
	v_xor_b32_e32 v112, 0x80000000, v247
	v_pk_add_f32 v[160:161], v[160:161], v[80:81] op_sel_hi:[1,0] neg_lo:[0,1] neg_hi:[0,1]
	v_pk_add_f32 v[144:145], v[144:145], v[80:81] op_sel_hi:[1,0] neg_lo:[0,1] neg_hi:[0,1]
	v_pk_add_f32 v[162:163], v[162:163], v[80:81] op_sel_hi:[1,0] neg_lo:[0,1] neg_hi:[0,1]
	v_pk_add_f32 v[146:147], v[146:147], v[80:81] op_sel_hi:[1,0] neg_lo:[0,1] neg_hi:[0,1]
	v_pk_add_f32 v[164:165], v[164:165], v[80:81] op_sel_hi:[1,0] neg_lo:[0,1] neg_hi:[0,1]
	v_pk_add_f32 v[148:149], v[148:149], v[80:81] op_sel_hi:[1,0] neg_lo:[0,1] neg_hi:[0,1]
	v_pk_add_f32 v[166:167], v[166:167], v[80:81] op_sel_hi:[1,0] neg_lo:[0,1] neg_hi:[0,1]
	v_pk_add_f32 v[150:151], v[150:151], v[80:81] op_sel_hi:[1,0] neg_lo:[0,1] neg_hi:[0,1]
	v_pk_add_f32 v[168:169], v[168:169], v[80:81] op_sel_hi:[1,0] neg_lo:[0,1] neg_hi:[0,1]
	v_pk_add_f32 v[152:153], v[152:153], v[80:81] op_sel_hi:[1,0] neg_lo:[0,1] neg_hi:[0,1]
	v_pk_add_f32 v[170:171], v[170:171], v[80:81] op_sel_hi:[1,0] neg_lo:[0,1] neg_hi:[0,1]
	v_pk_add_f32 v[154:155], v[154:155], v[80:81] op_sel_hi:[1,0] neg_lo:[0,1] neg_hi:[0,1]
	v_pk_add_f32 v[172:173], v[172:173], v[80:81] op_sel_hi:[1,0] neg_lo:[0,1] neg_hi:[0,1]
	v_pk_add_f32 v[156:157], v[156:157], v[80:81] op_sel_hi:[1,0] neg_lo:[0,1] neg_hi:[0,1]
	v_pk_add_f32 v[174:175], v[174:175], v[80:81] op_sel_hi:[1,0] neg_lo:[0,1] neg_hi:[0,1]
	v_pk_add_f32 v[158:159], v[158:159], v[80:81] op_sel_hi:[1,0] neg_lo:[0,1] neg_hi:[0,1]
	v_mul_f32_e32 v14, v14, v0
	v_mov_b32_e32 v113, v112
	v_mov_b32_e32 v114, v112
	v_mov_b32_e32 v115, v112
	v_mov_b32_e32 v116, v112
	v_mov_b32_e32 v117, v112
	v_mov_b32_e32 v118, v112
	v_mov_b32_e32 v119, v112
	v_mov_b32_e32 v120, v112
	v_mov_b32_e32 v121, v112
	v_mov_b32_e32 v122, v112
	v_mov_b32_e32 v123, v112
	v_mov_b32_e32 v124, v112
	v_mov_b32_e32 v125, v112
	v_mov_b32_e32 v126, v112
	v_mov_b32_e32 v127, v112
	v_mov_b32_e32 v96, v112
	v_mov_b32_e32 v97, v112
	v_mov_b32_e32 v98, v112
	v_mov_b32_e32 v99, v112
	v_mov_b32_e32 v100, v112
	v_mov_b32_e32 v101, v112
	v_mov_b32_e32 v102, v112
	v_mov_b32_e32 v103, v112
	v_mov_b32_e32 v104, v112
	v_mov_b32_e32 v105, v112
	v_mov_b32_e32 v106, v112
	v_mov_b32_e32 v107, v112
	v_mov_b32_e32 v108, v112
	v_mov_b32_e32 v109, v112
	v_mov_b32_e32 v110, v112
	v_mov_b32_e32 v111, v112
	s_branch .LBB0_568

.LBB0_568:
	s_min_u32 s34, s12, s4
	s_waitcnt vmcnt(2)
	ds_write_b128 v241, v[196:199] offset:9216
	s_waitcnt vmcnt(1)
	ds_write_b128 v240, v[200:203] offset:38912
	s_waitcnt vmcnt(0)
	ds_write_b128 v240, v[204:207] offset:49152
	s_lshl_b64 s[30:31], s[34:35], 13
	s_waitcnt lgkmcnt(0)
	s_barrier
	v_lshl_add_u64 v[80:81], v[224:225], 0, s[30:31]
	global_load_dwordx4 v[196:199], v[80:81], off
	global_load_dwordx4 v[200:203], v[218:219], off offset:-4096
	global_load_dwordx4 v[204:207], v[218:219], off
	ds_read_b128 v[176:179], v243 offset:13824
	ds_read_b128 v[80:83], v243 offset:9216
	ds_read_b128 v[180:183], v242 offset:59392
	s_waitcnt lgkmcnt(0)
	v_mfma_f32_32x32x16_bf16 v[128:143], v[80:83], v[180:183], v[112:127]
	ds_read_b128 v[184:187], v243 offset:9248
	v_exp_f32_e32 v15, v160
	v_exp_f32_e32 v80, v161
	ds_read_b128 v[248:251], v242 offset:60416
	v_add_f32_e32 v81, v80, v15
	v_cvt_pk_bf16_f32 v188, v15, v80
	v_exp_f32_e32 v15, v162
	v_exp_f32_e32 v80, v163
	ds_read_b128 v[160:163], v243 offset:13856
	v_add_f32_e32 v81, v15, v81
	v_cvt_pk_bf16_f32 v189, v15, v80
	v_add_f32_e32 v15, v80, v81
	v_mfma_f32_32x32x16_bf16 v[80:95], v[176:179], v[180:183], v[112:127]
	s_waitcnt lgkmcnt(1)
	v_mfma_f32_32x32x16_bf16 v[128:143], v[184:187], v[248:251], v[128:143]
	ds_read_b128 v[176:179], v243 offset:9280
	ds_read_b128 v[180:183], v242 offset:61440
	v_exp_f32_e32 v164, v164
	v_exp_f32_e32 v165, v165
	v_add_f32_e32 v15, v164, v15
	v_cvt_pk_bf16_f32 v190, v164, v165
	v_add_f32_e32 v15, v165, v15
	s_waitcnt lgkmcnt(2)
	v_mfma_f32_32x32x16_bf16 v[80:95], v[160:163], v[248:251], v[80:95]
	ds_read_b128 v[234:237], v243 offset:13888
	v_exp_f32_e32 v160, v166
	v_exp_f32_e32 v161, v167
	v_add_f32_e32 v15, v160, v15
	v_cvt_pk_bf16_f32 v191, v160, v161
	v_add_f32_e32 v15, v161, v15
	s_waitcnt lgkmcnt(1)
	v_mfma_f32_32x32x16_bf16 v[128:143], v[176:179], v[180:183], v[128:143]
	ds_read_b128 v[160:163], v243 offset:9312
	ds_read_b128 v[164:167], v242 offset:62464
	v_exp_f32_e32 v168, v168
	v_exp_f32_e32 v169, v169
	v_add_f32_e32 v15, v168, v15
	v_cvt_pk_bf16_f32 v184, v168, v169
	v_add_f32_e32 v15, v169, v15
	s_waitcnt lgkmcnt(2)
	v_mfma_f32_32x32x16_bf16 v[80:95], v[234:237], v[180:183], v[80:95]
	ds_read_b128 v[176:179], v243 offset:13920
	v_exp_f32_e32 v168, v170
	v_exp_f32_e32 v169, v171
	v_add_f32_e32 v15, v168, v15
	v_cvt_pk_bf16_f32 v185, v168, v169
	v_add_f32_e32 v15, v169, v15
	s_waitcnt lgkmcnt(1)
	v_mfma_f32_32x32x16_bf16 v[128:143], v[160:163], v[164:167], v[128:143]
	ds_read_b64_tr_b16 v[168:169], v244 offset:38912
	ds_read_b64_tr_b16 v[170:171], v244 offset:41472
	v_exp_f32_e32 v160, v172
	v_exp_f32_e32 v161, v173
	v_add_f32_e32 v15, v160, v15
	v_cvt_pk_bf16_f32 v186, v160, v161
	v_add_f32_e32 v15, v161, v15
	s_waitcnt lgkmcnt(2)
	v_mfma_f32_32x32x16_bf16 v[80:95], v[176:179], v[164:167], v[80:95]
	ds_read_b64_tr_b16 v[160:161], v244 offset:38976
	ds_read_b64_tr_b16 v[162:163], v244 offset:41536
	v_exp_f32_e32 v172, v174
	v_exp_f32_e32 v173, v175
	v_add_f32_e32 v15, v172, v15
	v_cvt_pk_bf16_f32 v187, v172, v173
	v_add_f32_e32 v15, v173, v15
	s_waitcnt lgkmcnt(2)
	v_mfma_f32_32x32x16_bf16 v[64:79], v[168:171], v[10:13], v[64:79]
	ds_read_b64_tr_b16 v[164:165], v244 offset:39040
	ds_read_b64_tr_b16 v[166:167], v244 offset:41600
	v_exp_f32_e32 v144, v144
	v_max3_f32 v172, v128, s33, v80
	v_add_f32_e32 v15, v144, v15
	s_waitcnt lgkmcnt(2)
	v_mfma_f32_32x32x16_bf16 v[48:63], v[160:163], v[10:13], v[48:63]
	ds_read_b64_tr_b16 v[168:169], v244 offset:39104
	v_exp_f32_e32 v145, v145
	ds_read_b64_tr_b16 v[170:171], v244 offset:41664
	v_cvt_pk_bf16_f32 v176, v144, v145
	v_max3_f32 v144, v172, v129, v81
	v_add_f32_e32 v15, v145, v15
	s_waitcnt lgkmcnt(2)
	v_mfma_f32_32x32x16_bf16 v[32:47], v[164:167], v[10:13], v[32:47]
	ds_read_b64_tr_b16 v[160:161], v244 offset:44032
	ds_read_b64_tr_b16 v[162:163], v244 offset:46592
	v_exp_f32_e32 v145, v146
	v_max3_f32 v144, v144, v130, v82
	v_add_f32_e32 v15, v145, v15
	s_waitcnt lgkmcnt(2)
	v_mfma_f32_32x32x16_bf16 v[16:31], v[168:171], v[10:13], v[16:31]
	ds_read_b64_tr_b16 v[164:165], v244 offset:44096
	ds_read_b64_tr_b16 v[166:167], v244 offset:46656
	v_exp_f32_e32 v10, v147
	v_max3_f32 v144, v144, v131, v83
	v_cvt_pk_bf16_f32 v177, v145, v10
	v_add_f32_e32 v15, v10, v15
	s_waitcnt lgkmcnt(2)
	v_mfma_f32_32x32x16_bf16 v[64:79], v[160:163], v[6:9], v[64:79]
	ds_read_b64_tr_b16 v[10:11], v244 offset:44160
	ds_read_b64_tr_b16 v[12:13], v244 offset:46720
	v_exp_f32_e32 v148, v148
	v_max3_f32 v160, v144, v132, v84
	v_add_f32_e32 v15, v148, v15
	s_waitcnt lgkmcnt(2)
	v_mfma_f32_32x32x16_bf16 v[48:63], v[164:167], v[6:9], v[48:63]
	ds_read_b64_tr_b16 v[144:145], v244 offset:44224
	v_exp_f32_e32 v149, v149
	ds_read_b64_tr_b16 v[146:147], v244 offset:46784
	v_cvt_pk_bf16_f32 v178, v148, v149
	v_max3_f32 v148, v160, v133, v85
	v_add_f32_e32 v15, v149, v15
	s_waitcnt lgkmcnt(2)
	v_mfma_f32_32x32x16_bf16 v[32:47], v[10:13], v[6:9], v[32:47]
	ds_read_b64_tr_b16 v[160:161], v244 offset:49152
	ds_read_b64_tr_b16 v[162:163], v244 offset:51712
	v_exp_f32_e32 v149, v150
	v_max3_f32 v148, v148, v134, v86
	v_add_f32_e32 v15, v149, v15
	s_waitcnt lgkmcnt(2)
	v_mfma_f32_32x32x16_bf16 v[16:31], v[144:147], v[6:9], v[16:31]
	ds_read_b64_tr_b16 v[10:11], v244 offset:49216
	ds_read_b64_tr_b16 v[12:13], v244 offset:51776
	v_exp_f32_e32 v6, v151
	v_max3_f32 v144, v148, v135, v87
	v_cvt_pk_bf16_f32 v179, v149, v6
	v_add_f32_e32 v15, v6, v15
	s_waitcnt lgkmcnt(2)
	v_mfma_f32_32x32x16_bf16 v[64:79], v[160:163], v[2:5], v[64:79]
	ds_read_b64_tr_b16 v[6:7], v244 offset:49280
	ds_read_b64_tr_b16 v[8:9], v244 offset:51840
	v_exp_f32_e32 v148, v152
	v_max3_f32 v149, v144, v136, v88
	v_add_f32_e32 v15, v148, v15
	s_waitcnt lgkmcnt(2)
	v_mfma_f32_32x32x16_bf16 v[48:63], v[10:13], v[2:5], v[48:63]
	ds_read_b64_tr_b16 v[144:145], v244 offset:49344
	v_exp_f32_e32 v10, v153
	ds_read_b64_tr_b16 v[146:147], v244 offset:51904
	v_cvt_pk_bf16_f32 v180, v148, v10
	v_max3_f32 v148, v149, v137, v89
	v_add_f32_e32 v15, v10, v15
	s_waitcnt lgkmcnt(2)
	v_mfma_f32_32x32x16_bf16 v[32:47], v[6:9], v[2:5], v[32:47]
	ds_read_b64_tr_b16 v[10:11], v244 offset:54272
	ds_read_b64_tr_b16 v[12:13], v244 offset:56832
	v_exp_f32_e32 v149, v154
	v_max3_f32 v148, v148, v138, v90
	v_add_f32_e32 v15, v149, v15
	s_waitcnt lgkmcnt(2)
	v_mfma_f32_32x32x16_bf16 v[16:31], v[144:147], v[2:5], v[16:31]
	ds_read_b64_tr_b16 v[6:7], v244 offset:54336
	ds_read_b64_tr_b16 v[8:9], v244 offset:56896
	v_exp_f32_e32 v2, v155
	v_max3_f32 v144, v148, v139, v91
	v_cvt_pk_bf16_f32 v181, v149, v2
	v_add_f32_e32 v15, v2, v15
	s_waitcnt lgkmcnt(2)
	v_mfma_f32_32x32x16_bf16 v[64:79], v[10:13], v[192:195], v[64:79]
	ds_read_b64_tr_b16 v[2:3], v244 offset:54400
	ds_read_b64_tr_b16 v[4:5], v244 offset:56960
	v_exp_f32_e32 v145, v156
	v_max3_f32 v144, v144, v140, v92
	v_add_f32_e32 v15, v145, v15
	s_waitcnt lgkmcnt(2)
	v_mfma_f32_32x32x16_bf16 v[48:63], v[6:9], v[192:195], v[48:63]
	ds_read_b64_tr_b16 v[10:11], v244 offset:54464
	v_exp_f32_e32 v6, v157
	ds_read_b64_tr_b16 v[12:13], v244 offset:57024
	v_add_f32_e32 v7, v6, v15
	v_cvt_pk_bf16_f32 v182, v145, v6
	v_max3_f32 v6, v144, v141, v93
	s_waitcnt lgkmcnt(2)
	v_mfma_f32_32x32x16_bf16 v[32:47], v[2:5], v[192:195], v[32:47]
	v_exp_f32_e32 v3, v158
	v_max3_f32 v4, v6, v142, v94
	v_add_f32_e32 v2, v3, v7
	s_waitcnt lgkmcnt(0)
	v_mfma_f32_32x32x16_bf16 v[16:31], v[10:13], v[192:195], v[16:31]
	v_exp_f32_e32 v5, v159
	v_cmp_gt_f32_e32 vcc, 1.0, v0
	v_add_f32_e32 v2, v5, v2
	v_mov_b32_e32 v239, v2
	v_cvt_pk_bf16_f32 v183, v3, v5
	v_max3_f32 v3, v4, v143, v95
	v_permlane32_swap_b32_e32 v2, v239
	s_cbranch_vccz .LBB0_570
	v_pk_mul_f32 v[78:79], v[0:1], v[78:79] op_sel_hi:[0,1]
	v_pk_mul_f32 v[76:77], v[0:1], v[76:77] op_sel_hi:[0,1]
	v_pk_mul_f32 v[74:75], v[0:1], v[74:75] op_sel_hi:[0,1]
	v_pk_mul_f32 v[72:73], v[0:1], v[72:73] op_sel_hi:[0,1]
	v_pk_mul_f32 v[70:71], v[0:1], v[70:71] op_sel_hi:[0,1]
	v_pk_mul_f32 v[68:69], v[0:1], v[68:69] op_sel_hi:[0,1]
	v_pk_mul_f32 v[66:67], v[0:1], v[66:67] op_sel_hi:[0,1]
	v_pk_mul_f32 v[64:65], v[0:1], v[64:65] op_sel_hi:[0,1]
	v_pk_mul_f32 v[62:63], v[0:1], v[62:63] op_sel_hi:[0,1]
	v_pk_mul_f32 v[60:61], v[0:1], v[60:61] op_sel_hi:[0,1]
	v_pk_mul_f32 v[58:59], v[0:1], v[58:59] op_sel_hi:[0,1]
	v_pk_mul_f32 v[56:57], v[0:1], v[56:57] op_sel_hi:[0,1]
	v_pk_mul_f32 v[54:55], v[0:1], v[54:55] op_sel_hi:[0,1]
	v_pk_mul_f32 v[52:53], v[0:1], v[52:53] op_sel_hi:[0,1]
	v_pk_mul_f32 v[50:51], v[0:1], v[50:51] op_sel_hi:[0,1]
	v_pk_mul_f32 v[48:49], v[0:1], v[48:49] op_sel_hi:[0,1]
	v_pk_mul_f32 v[46:47], v[0:1], v[46:47] op_sel_hi:[0,1]
	v_pk_mul_f32 v[44:45], v[0:1], v[44:45] op_sel_hi:[0,1]
	v_pk_mul_f32 v[42:43], v[0:1], v[42:43] op_sel_hi:[0,1]
	v_pk_mul_f32 v[40:41], v[0:1], v[40:41] op_sel_hi:[0,1]
	v_pk_mul_f32 v[38:39], v[0:1], v[38:39] op_sel_hi:[0,1]
	v_pk_mul_f32 v[36:37], v[0:1], v[36:37] op_sel_hi:[0,1]
	v_pk_mul_f32 v[34:35], v[0:1], v[34:35] op_sel_hi:[0,1]
	v_pk_mul_f32 v[32:33], v[0:1], v[32:33] op_sel_hi:[0,1]
	v_pk_mul_f32 v[30:31], v[0:1], v[30:31] op_sel_hi:[0,1]
	v_pk_mul_f32 v[28:29], v[0:1], v[28:29] op_sel_hi:[0,1]
	v_pk_mul_f32 v[26:27], v[0:1], v[26:27] op_sel_hi:[0,1]
	v_pk_mul_f32 v[24:25], v[0:1], v[24:25] op_sel_hi:[0,1]
	v_pk_mul_f32 v[22:23], v[0:1], v[22:23] op_sel_hi:[0,1]
	v_pk_mul_f32 v[20:21], v[0:1], v[20:21] op_sel_hi:[0,1]
	v_pk_mul_f32 v[18:19], v[0:1], v[18:19] op_sel_hi:[0,1]
	v_pk_mul_f32 v[16:17], v[0:1], v[16:17] op_sel_hi:[0,1]
.LBB0_570:
	v_add_f32_e32 v0, v2, v239
	v_add_f32_e32 v248, v14, v0
	v_mov_b32_e32 v0, v3
	s_cmp_ge_u32 s13, s16
	v_mov_b32_e32 v226, 1.0
	v_permlane32_swap_b32_e32 v3, v0
	s_cbranch_scc1 .LBB0_574
	v_max_f32_e32 v2, v3, v3
	v_max_f32_e32 v0, v0, v0
	v_max_f32_e32 v0, v2, v0
	v_cmp_lt_f32_e32 vcc, s28, v0
	s_cbranch_vccz .LBB0_573
	v_max_f32_e32 v0, v0, v0
	v_max_f32_e32 v0, 0, v0
	v_exp_f32_e64 v226, -v0
	v_add_f32_e32 v247, v247, v0
	v_xor_b32_e32 v112, 0x80000000, v247
	v_sub_f32_e32 v143, v143, v0
	v_sub_f32_e32 v142, v142, v0
	v_sub_f32_e32 v141, v141, v0
	v_sub_f32_e32 v140, v140, v0
	v_sub_f32_e32 v139, v139, v0
	v_sub_f32_e32 v138, v138, v0
	v_sub_f32_e32 v137, v137, v0
	v_sub_f32_e32 v136, v136, v0
	v_sub_f32_e32 v135, v135, v0
	v_sub_f32_e32 v134, v134, v0
	v_sub_f32_e32 v133, v133, v0
	v_sub_f32_e32 v132, v132, v0
	v_sub_f32_e32 v131, v131, v0
	v_sub_f32_e32 v130, v130, v0
	v_sub_f32_e32 v129, v129, v0
	v_sub_f32_e32 v128, v128, v0
	v_sub_f32_e32 v95, v95, v0
	v_sub_f32_e32 v94, v94, v0
	v_sub_f32_e32 v93, v93, v0
	v_sub_f32_e32 v92, v92, v0
	v_sub_f32_e32 v91, v91, v0
	v_sub_f32_e32 v90, v90, v0
	v_sub_f32_e32 v89, v89, v0
	v_sub_f32_e32 v88, v88, v0
	v_sub_f32_e32 v87, v87, v0
	v_sub_f32_e32 v86, v86, v0
	v_sub_f32_e32 v85, v85, v0
	v_sub_f32_e32 v84, v84, v0
	v_sub_f32_e32 v83, v83, v0
	v_sub_f32_e32 v82, v82, v0
	v_sub_f32_e32 v81, v81, v0
	v_sub_f32_e32 v80, v80, v0
	v_mul_f32_e32 v248, v248, v226
	v_mov_b32_e32 v113, v112
	v_mov_b32_e32 v114, v112
	v_mov_b32_e32 v115, v112
	v_mov_b32_e32 v116, v112
	v_mov_b32_e32 v117, v112
	v_mov_b32_e32 v118, v112
	v_mov_b32_e32 v119, v112
	v_mov_b32_e32 v120, v112
	v_mov_b32_e32 v121, v112
	v_mov_b32_e32 v122, v112
	v_mov_b32_e32 v123, v112
	v_mov_b32_e32 v124, v112
	v_mov_b32_e32 v125, v112
	v_mov_b32_e32 v126, v112
	v_mov_b32_e32 v127, v112
	v_mov_b32_e32 v111, v112
	v_mov_b32_e32 v110, v112
	v_mov_b32_e32 v109, v112
	v_mov_b32_e32 v108, v112
	v_mov_b32_e32 v107, v112
	v_mov_b32_e32 v106, v112
	v_mov_b32_e32 v105, v112
	v_mov_b32_e32 v104, v112
	v_mov_b32_e32 v103, v112
	v_mov_b32_e32 v102, v112
	v_mov_b32_e32 v101, v112
	v_mov_b32_e32 v100, v112
	v_mov_b32_e32 v99, v112
	v_mov_b32_e32 v98, v112
	v_mov_b32_e32 v97, v112
	v_mov_b32_e32 v96, v112
	s_branch .LBB0_574

.LBB0_582:
	s_add_i32 s13, s12, -1
	s_min_u32 s34, s13, s4
	s_lshl_b64 s[30:31], s[34:35], 13
	v_lshl_add_u64 v[2:3], v[216:217], 0, s[30:31]
	global_load_dwordx4 v[196:199], v[2:3], off
	v_add_co_u32_e32 v2, vcc, s1, v212
	ds_read_b128 v[6:9], v243
	ds_read_b128 v[12:15], v242 offset:59392
	v_addc_co_u32_e32 v3, vcc, -1, v213, vcc
	global_load_dwordx4 v[200:203], v[2:3], off offset:-4096
	global_load_dwordx4 v[204:207], v[2:3], off
	ds_read_b128 v[2:5], v243 offset:4608
	s_waitcnt lgkmcnt(0)
	v_mfma_f32_32x32x16_bf16 v[160:175], v[6:9], v[12:15], v[96:111]
	ds_read_b128 v[112:115], v243 offset:32
	v_exp_f32_e32 v0, v128
	v_exp_f32_e32 v6, v129
	ds_read_b128 v[116:119], v242 offset:60416
	v_add_f32_e32 v11, v6, v0
	v_cvt_pk_bf16_f32 v10, v0, v6
	v_mfma_f32_32x32x16_bf16 v[144:159], v[2:5], v[12:15], v[96:111]
	ds_read_b128 v[6:9], v243 offset:4640
	v_exp_f32_e32 v0, v130
	v_exp_f32_e32 v120, v131
	v_add_f32_e32 v121, v0, v11
	v_cvt_pk_bf16_f32 v11, v0, v120
	v_add_f32_e32 v0, v120, v121
	s_waitcnt lgkmcnt(1)
	v_mfma_f32_32x32x16_bf16 v[160:175], v[112:115], v[116:119], v[160:175]
	ds_read_b128 v[2:5], v243 offset:64
	ds_read_b128 v[120:123], v242 offset:61440
	v_exp_f32_e32 v12, v132
	v_exp_f32_e32 v13, v133
	v_add_f32_e32 v0, v12, v0
	v_add_f32_e32 v0, v13, v0
	v_cvt_pk_bf16_f32 v12, v12, v13
	s_waitcnt lgkmcnt(2)
	v_mfma_f32_32x32x16_bf16 v[144:159], v[6:9], v[116:119], v[144:159]
	ds_read_b128 v[112:115], v243 offset:4672
	v_exp_f32_e32 v6, v134
	v_exp_f32_e32 v7, v135
	v_add_f32_e32 v0, v6, v0
	v_add_f32_e32 v0, v7, v0
	v_cvt_pk_bf16_f32 v13, v6, v7
	s_waitcnt lgkmcnt(1)
	v_mfma_f32_32x32x16_bf16 v[160:175], v[2:5], v[120:123], v[160:175]
	ds_read_b128 v[116:119], v243 offset:96
	ds_read_b128 v[124:127], v242 offset:62464
	v_exp_f32_e32 v2, v136
	v_exp_f32_e32 v3, v137
	v_add_f32_e32 v0, v2, v0
	v_add_f32_e32 v0, v3, v0
	v_cvt_pk_bf16_f32 v6, v2, v3
	s_waitcnt lgkmcnt(2)
	v_mfma_f32_32x32x16_bf16 v[144:159], v[112:115], v[120:123], v[144:159]
	ds_read_b128 v[2:5], v243 offset:4704
	v_exp_f32_e32 v7, v138
	v_exp_f32_e32 v8, v139
	v_add_f32_e32 v0, v7, v0
	v_add_f32_e32 v0, v8, v0
	v_cvt_pk_bf16_f32 v7, v7, v8
	s_waitcnt lgkmcnt(1)
	v_mfma_f32_32x32x16_bf16 v[160:175], v[116:119], v[124:127], v[160:175]
	ds_read_b64_tr_b16 v[112:113], v244 offset:18432
	ds_read_b64_tr_b16 v[114:115], v244 offset:20992
	v_exp_f32_e32 v8, v140
	v_exp_f32_e32 v9, v141
	v_add_f32_e32 v0, v8, v0
	v_add_f32_e32 v0, v9, v0
	v_cvt_pk_bf16_f32 v8, v8, v9
	s_waitcnt lgkmcnt(2)
	v_mfma_f32_32x32x16_bf16 v[144:159], v[2:5], v[124:127], v[144:159]
	ds_read_b64_tr_b16 v[116:117], v244 offset:18496
	ds_read_b64_tr_b16 v[118:119], v244 offset:21056
	v_exp_f32_e32 v9, v142
	v_exp_f32_e32 v14, v143
	v_add_f32_e32 v0, v9, v0
	v_add_f32_e32 v0, v14, v0
	v_cvt_pk_bf16_f32 v9, v9, v14
	s_waitcnt lgkmcnt(2)
	v_mfma_f32_32x32x16_bf16 v[64:79], v[112:115], v[188:191], v[64:79]
	ds_read_b64_tr_b16 v[120:121], v244 offset:18560
	ds_read_b64_tr_b16 v[122:123], v244 offset:21120
	v_exp_f32_e32 v2, v80
	v_max3_f32 v3, v160, s33, v144
	v_add_f32_e32 v0, v2, v0
	s_waitcnt lgkmcnt(2)
	v_mfma_f32_32x32x16_bf16 v[48:63], v[116:119], v[188:191], v[48:63]
	ds_read_b64_tr_b16 v[112:113], v244 offset:18624
	ds_read_b64_tr_b16 v[114:115], v244 offset:21184
	v_exp_f32_e32 v4, v81
	v_max3_f32 v3, v3, v161, v145
	v_add_f32_e32 v0, v4, v0
	v_cvt_pk_bf16_f32 v2, v2, v4
	s_waitcnt lgkmcnt(2)
	v_mfma_f32_32x32x16_bf16 v[32:47], v[120:123], v[188:191], v[32:47]
	ds_read_b64_tr_b16 v[116:117], v244 offset:23552
	ds_read_b64_tr_b16 v[118:119], v244 offset:26112
	v_exp_f32_e32 v4, v82
	v_max3_f32 v5, v3, v162, v146
	v_add_f32_e32 v0, v4, v0
	s_waitcnt lgkmcnt(2)
	v_mfma_f32_32x32x16_bf16 v[16:31], v[112:115], v[188:191], v[16:31]
	ds_read_b64_tr_b16 v[120:121], v244 offset:23616
	v_exp_f32_e32 v3, v83
	ds_read_b64_tr_b16 v[122:123], v244 offset:26176
	v_add_f32_e32 v0, v3, v0
	v_cvt_pk_bf16_f32 v3, v4, v3
	v_max3_f32 v4, v5, v163, v147
	s_waitcnt lgkmcnt(2)
	v_mfma_f32_32x32x16_bf16 v[64:79], v[116:119], v[184:187], v[64:79]
	ds_read_b64_tr_b16 v[80:81], v244 offset:23680
	ds_read_b64_tr_b16 v[82:83], v244 offset:26240
	v_exp_f32_e32 v5, v84
	v_max3_f32 v14, v4, v164, v148
	v_add_f32_e32 v0, v5, v0
	s_waitcnt lgkmcnt(2)
	v_mfma_f32_32x32x16_bf16 v[48:63], v[120:123], v[184:187], v[48:63]
	ds_read_b64_tr_b16 v[112:113], v244 offset:23744
	v_exp_f32_e32 v4, v85
	ds_read_b64_tr_b16 v[114:115], v244 offset:26304
	v_add_f32_e32 v0, v4, v0
	v_cvt_pk_bf16_f32 v4, v5, v4
	v_max3_f32 v5, v14, v165, v149
	s_waitcnt lgkmcnt(2)
	v_mfma_f32_32x32x16_bf16 v[32:47], v[80:83], v[184:187], v[32:47]
	ds_read_b64_tr_b16 v[116:117], v244 offset:28672
	ds_read_b64_tr_b16 v[118:119], v244 offset:31232
	v_exp_f32_e32 v14, v86
	v_max3_f32 v15, v5, v166, v150
	v_add_f32_e32 v0, v14, v0
	s_waitcnt lgkmcnt(2)
	v_mfma_f32_32x32x16_bf16 v[16:31], v[112:115], v[184:187], v[16:31]
	ds_read_b64_tr_b16 v[80:81], v244 offset:28736
	v_exp_f32_e32 v5, v87
	ds_read_b64_tr_b16 v[82:83], v244 offset:31296
	v_add_f32_e32 v0, v5, v0
	v_cvt_pk_bf16_f32 v5, v14, v5
	v_max3_f32 v14, v15, v167, v151
	s_waitcnt lgkmcnt(2)
	v_mfma_f32_32x32x16_bf16 v[64:79], v[116:119], v[176:179], v[64:79]
	ds_read_b64_tr_b16 v[84:85], v244 offset:28800
	ds_read_b64_tr_b16 v[86:87], v244 offset:31360
	v_exp_f32_e32 v15, v88
	v_max3_f32 v14, v14, v168, v152
	v_add_f32_e32 v0, v15, v0
	s_waitcnt lgkmcnt(2)
	v_mfma_f32_32x32x16_bf16 v[48:63], v[80:83], v[176:179], v[48:63]
	ds_read_b64_tr_b16 v[112:113], v244 offset:28864
	ds_read_b64_tr_b16 v[114:115], v244 offset:31424
	v_exp_f32_e32 v80, v89
	v_max3_f32 v14, v14, v169, v153
	v_add_f32_e32 v0, v80, v0
	v_cvt_pk_bf16_f32 v192, v15, v80
	s_waitcnt lgkmcnt(2)
	v_mfma_f32_32x32x16_bf16 v[32:47], v[84:87], v[176:179], v[32:47]
	ds_read_b64_tr_b16 v[80:81], v244 offset:33792
	ds_read_b64_tr_b16 v[82:83], v244 offset:36352
	v_exp_f32_e32 v15, v90
	v_max3_f32 v14, v14, v170, v154
	v_add_f32_e32 v0, v15, v0
	s_waitcnt lgkmcnt(2)
	v_mfma_f32_32x32x16_bf16 v[16:31], v[112:115], v[176:179], v[16:31]
	ds_read_b64_tr_b16 v[84:85], v244 offset:33856
	ds_read_b64_tr_b16 v[86:87], v244 offset:36416
	v_exp_f32_e32 v88, v91
	v_max3_f32 v14, v14, v171, v155
	v_add_f32_e32 v0, v88, v0
	v_cvt_pk_bf16_f32 v193, v15, v88
	s_waitcnt lgkmcnt(2)
	v_mfma_f32_32x32x16_bf16 v[64:79], v[80:83], v[180:183], v[64:79]
	ds_read_b64_tr_b16 v[88:89], v244 offset:33920
	ds_read_b64_tr_b16 v[90:91], v244 offset:36480
	v_exp_f32_e32 v15, v92
	v_max3_f32 v14, v14, v172, v156
	v_add_f32_e32 v0, v15, v0
	s_waitcnt lgkmcnt(2)
	v_mfma_f32_32x32x16_bf16 v[48:63], v[84:87], v[180:183], v[48:63]
	ds_read_b64_tr_b16 v[80:81], v244 offset:33984
	ds_read_b64_tr_b16 v[82:83], v244 offset:36544
	v_exp_f32_e32 v84, v93
	v_max3_f32 v14, v14, v173, v157
	v_add_f32_e32 v0, v84, v0
	v_cvt_pk_bf16_f32 v194, v15, v84
	s_waitcnt lgkmcnt(2)
	v_mfma_f32_32x32x16_bf16 v[32:47], v[88:91], v[180:183], v[32:47]
	v_exp_f32_e32 v15, v94
	v_max3_f32 v14, v14, v174, v158
	v_add_f32_e32 v0, v15, v0
	s_waitcnt lgkmcnt(0)
	v_mfma_f32_32x32x16_bf16 v[16:31], v[80:83], v[180:183], v[16:31]
	v_exp_f32_e32 v80, v95
	v_cmp_gt_f32_e32 vcc, 1.0, v220
	v_add_f32_e32 v0, v80, v0
	v_mov_b32_e32 v239, v0
	v_cvt_pk_bf16_f32 v195, v15, v80
	v_max3_f32 v15, v14, v175, v159
	v_permlane32_swap_b32_e32 v0, v239
	s_cbranch_vccz .LBB0_584
	v_pk_mul_f32 v[78:79], v[220:221], v[78:79] op_sel_hi:[0,1]
	v_pk_mul_f32 v[76:77], v[220:221], v[76:77] op_sel_hi:[0,1]
	v_pk_mul_f32 v[74:75], v[220:221], v[74:75] op_sel_hi:[0,1]
	v_pk_mul_f32 v[72:73], v[220:221], v[72:73] op_sel_hi:[0,1]
	v_pk_mul_f32 v[70:71], v[220:221], v[70:71] op_sel_hi:[0,1]
	v_pk_mul_f32 v[68:69], v[220:221], v[68:69] op_sel_hi:[0,1]
	v_pk_mul_f32 v[66:67], v[220:221], v[66:67] op_sel_hi:[0,1]
	v_pk_mul_f32 v[64:65], v[220:221], v[64:65] op_sel_hi:[0,1]
	v_pk_mul_f32 v[62:63], v[220:221], v[62:63] op_sel_hi:[0,1]
	v_pk_mul_f32 v[60:61], v[220:221], v[60:61] op_sel_hi:[0,1]
	v_pk_mul_f32 v[58:59], v[220:221], v[58:59] op_sel_hi:[0,1]
	v_pk_mul_f32 v[56:57], v[220:221], v[56:57] op_sel_hi:[0,1]
	v_pk_mul_f32 v[54:55], v[220:221], v[54:55] op_sel_hi:[0,1]
	v_pk_mul_f32 v[52:53], v[220:221], v[52:53] op_sel_hi:[0,1]
	v_pk_mul_f32 v[50:51], v[220:221], v[50:51] op_sel_hi:[0,1]
	v_pk_mul_f32 v[48:49], v[220:221], v[48:49] op_sel_hi:[0,1]
	v_pk_mul_f32 v[46:47], v[220:221], v[46:47] op_sel_hi:[0,1]
	v_pk_mul_f32 v[44:45], v[220:221], v[44:45] op_sel_hi:[0,1]
	v_pk_mul_f32 v[42:43], v[220:221], v[42:43] op_sel_hi:[0,1]
	v_pk_mul_f32 v[40:41], v[220:221], v[40:41] op_sel_hi:[0,1]
	v_pk_mul_f32 v[38:39], v[220:221], v[38:39] op_sel_hi:[0,1]
	v_pk_mul_f32 v[36:37], v[220:221], v[36:37] op_sel_hi:[0,1]
	v_pk_mul_f32 v[34:35], v[220:221], v[34:35] op_sel_hi:[0,1]
	v_pk_mul_f32 v[32:33], v[220:221], v[32:33] op_sel_hi:[0,1]
	v_pk_mul_f32 v[30:31], v[220:221], v[30:31] op_sel_hi:[0,1]
	v_pk_mul_f32 v[28:29], v[220:221], v[28:29] op_sel_hi:[0,1]
	v_pk_mul_f32 v[26:27], v[220:221], v[26:27] op_sel_hi:[0,1]
	v_pk_mul_f32 v[24:25], v[220:221], v[24:25] op_sel_hi:[0,1]
	v_pk_mul_f32 v[22:23], v[220:221], v[22:23] op_sel_hi:[0,1]
	v_pk_mul_f32 v[20:21], v[220:221], v[20:21] op_sel_hi:[0,1]
	v_pk_mul_f32 v[18:19], v[220:221], v[18:19] op_sel_hi:[0,1]
	v_pk_mul_f32 v[16:17], v[220:221], v[16:17] op_sel_hi:[0,1]
.LBB0_584:
	v_mov_b32_e32 v238, v15
	v_add_f32_e32 v0, v0, v239
	v_add_f32_e32 v14, v222, v0
	v_permlane32_swap_b32_e32 v15, v238
	v_max_f32_e32 v0, v238, v238
	v_max_f32_e32 v15, v15, v15
	v_max_f32_e32 v0, v15, v0
	v_cmp_lt_f32_e32 vcc, s28, v0
	s_cbranch_vccz .LBB0_586
	v_max_f32_e32 v0, v0, v0
	v_max_f32_e32 v80, 0, v0
	v_exp_f32_e64 v0, -v80
	v_add_f32_e32 v221, v221, v80
	v_xor_b32_e32 v112, 0x80000000, v221
	v_pk_add_f32 v[160:161], v[160:161], v[80:81] op_sel_hi:[1,0] neg_lo:[0,1] neg_hi:[0,1]
	v_pk_add_f32 v[144:145], v[144:145], v[80:81] op_sel_hi:[1,0] neg_lo:[0,1] neg_hi:[0,1]
	v_pk_add_f32 v[162:163], v[162:163], v[80:81] op_sel_hi:[1,0] neg_lo:[0,1] neg_hi:[0,1]
	v_pk_add_f32 v[146:147], v[146:147], v[80:81] op_sel_hi:[1,0] neg_lo:[0,1] neg_hi:[0,1]
	v_pk_add_f32 v[164:165], v[164:165], v[80:81] op_sel_hi:[1,0] neg_lo:[0,1] neg_hi:[0,1]
	v_pk_add_f32 v[148:149], v[148:149], v[80:81] op_sel_hi:[1,0] neg_lo:[0,1] neg_hi:[0,1]
	v_pk_add_f32 v[166:167], v[166:167], v[80:81] op_sel_hi:[1,0] neg_lo:[0,1] neg_hi:[0,1]
	v_pk_add_f32 v[150:151], v[150:151], v[80:81] op_sel_hi:[1,0] neg_lo:[0,1] neg_hi:[0,1]
	v_pk_add_f32 v[168:169], v[168:169], v[80:81] op_sel_hi:[1,0] neg_lo:[0,1] neg_hi:[0,1]
	v_pk_add_f32 v[152:153], v[152:153], v[80:81] op_sel_hi:[1,0] neg_lo:[0,1] neg_hi:[0,1]
	v_pk_add_f32 v[170:171], v[170:171], v[80:81] op_sel_hi:[1,0] neg_lo:[0,1] neg_hi:[0,1]
	v_pk_add_f32 v[154:155], v[154:155], v[80:81] op_sel_hi:[1,0] neg_lo:[0,1] neg_hi:[0,1]
	v_pk_add_f32 v[172:173], v[172:173], v[80:81] op_sel_hi:[1,0] neg_lo:[0,1] neg_hi:[0,1]
	v_pk_add_f32 v[156:157], v[156:157], v[80:81] op_sel_hi:[1,0] neg_lo:[0,1] neg_hi:[0,1]
	v_pk_add_f32 v[174:175], v[174:175], v[80:81] op_sel_hi:[1,0] neg_lo:[0,1] neg_hi:[0,1]
	v_pk_add_f32 v[158:159], v[158:159], v[80:81] op_sel_hi:[1,0] neg_lo:[0,1] neg_hi:[0,1]
	v_mul_f32_e32 v14, v14, v0
	v_mov_b32_e32 v113, v112
	v_mov_b32_e32 v114, v112
	v_mov_b32_e32 v115, v112
	v_mov_b32_e32 v116, v112
	v_mov_b32_e32 v117, v112
	v_mov_b32_e32 v118, v112
	v_mov_b32_e32 v119, v112
	v_mov_b32_e32 v120, v112
	v_mov_b32_e32 v121, v112
	v_mov_b32_e32 v122, v112
	v_mov_b32_e32 v123, v112
	v_mov_b32_e32 v124, v112
	v_mov_b32_e32 v125, v112
	v_mov_b32_e32 v126, v112
	v_mov_b32_e32 v127, v112
	v_mov_b32_e32 v96, v112
	v_mov_b32_e32 v97, v112
	v_mov_b32_e32 v98, v112
	v_mov_b32_e32 v99, v112
	v_mov_b32_e32 v100, v112
	v_mov_b32_e32 v101, v112
	v_mov_b32_e32 v102, v112
	v_mov_b32_e32 v103, v112
	v_mov_b32_e32 v104, v112
	v_mov_b32_e32 v105, v112
	v_mov_b32_e32 v106, v112
	v_mov_b32_e32 v107, v112
	v_mov_b32_e32 v108, v112
	v_mov_b32_e32 v109, v112
	v_mov_b32_e32 v110, v112
	v_mov_b32_e32 v111, v112
	s_branch .LBB0_587

.LBB0_587:
	s_min_u32 s34, s12, s4
	s_waitcnt vmcnt(2)
	ds_write_b128 v241, v[196:199] offset:9216
	s_waitcnt vmcnt(1)
	ds_write_b128 v240, v[200:203] offset:38912
	s_waitcnt vmcnt(0)
	ds_write_b128 v240, v[204:207] offset:49152
	s_lshl_b64 s[30:31], s[34:35], 13
	s_waitcnt lgkmcnt(0)
	s_barrier
	v_lshl_add_u64 v[80:81], v[216:217], 0, s[30:31]
	global_load_dwordx4 v[196:199], v[80:81], off
	global_load_dwordx4 v[200:203], v[212:213], off offset:-4096
	global_load_dwordx4 v[204:207], v[212:213], off
	ds_read_b128 v[176:179], v243 offset:13824
	ds_read_b128 v[80:83], v243 offset:9216
	ds_read_b128 v[180:183], v242 offset:59392
	s_waitcnt lgkmcnt(0)
	v_mfma_f32_32x32x16_bf16 v[128:143], v[80:83], v[180:183], v[112:127]
	ds_read_b128 v[184:187], v243 offset:9248
	v_exp_f32_e32 v15, v160
	v_exp_f32_e32 v80, v161
	ds_read_b128 v[222:225], v242 offset:60416
	v_add_f32_e32 v81, v80, v15
	v_cvt_pk_bf16_f32 v188, v15, v80
	v_exp_f32_e32 v15, v162
	v_exp_f32_e32 v80, v163
	ds_read_b128 v[160:163], v243 offset:13856
	v_add_f32_e32 v81, v15, v81
	v_cvt_pk_bf16_f32 v189, v15, v80
	v_add_f32_e32 v15, v80, v81
	v_mfma_f32_32x32x16_bf16 v[80:95], v[176:179], v[180:183], v[112:127]
	s_waitcnt lgkmcnt(1)
	v_mfma_f32_32x32x16_bf16 v[128:143], v[184:187], v[222:225], v[128:143]
	ds_read_b128 v[176:179], v243 offset:9280
	ds_read_b128 v[180:183], v242 offset:61440
	v_exp_f32_e32 v164, v164
	v_exp_f32_e32 v165, v165
	v_add_f32_e32 v15, v164, v15
	v_cvt_pk_bf16_f32 v190, v164, v165
	v_add_f32_e32 v15, v165, v15
	s_waitcnt lgkmcnt(2)
	v_mfma_f32_32x32x16_bf16 v[80:95], v[160:163], v[222:225], v[80:95]
	ds_read_b128 v[234:237], v243 offset:13888
	v_exp_f32_e32 v160, v166
	v_exp_f32_e32 v161, v167
	v_add_f32_e32 v15, v160, v15
	v_cvt_pk_bf16_f32 v191, v160, v161
	v_add_f32_e32 v15, v161, v15
	s_waitcnt lgkmcnt(1)
	v_mfma_f32_32x32x16_bf16 v[128:143], v[176:179], v[180:183], v[128:143]
	ds_read_b128 v[160:163], v243 offset:9312
	ds_read_b128 v[164:167], v242 offset:62464
	v_exp_f32_e32 v168, v168
	v_exp_f32_e32 v169, v169
	v_add_f32_e32 v15, v168, v15
	v_cvt_pk_bf16_f32 v184, v168, v169
	v_add_f32_e32 v15, v169, v15
	s_waitcnt lgkmcnt(2)
	v_mfma_f32_32x32x16_bf16 v[80:95], v[234:237], v[180:183], v[80:95]
	ds_read_b128 v[176:179], v243 offset:13920
	v_exp_f32_e32 v168, v170
	v_exp_f32_e32 v169, v171
	v_add_f32_e32 v15, v168, v15
	v_cvt_pk_bf16_f32 v185, v168, v169
	v_add_f32_e32 v15, v169, v15
	s_waitcnt lgkmcnt(1)
	v_mfma_f32_32x32x16_bf16 v[128:143], v[160:163], v[164:167], v[128:143]
	ds_read_b64_tr_b16 v[168:169], v244 offset:38912
	ds_read_b64_tr_b16 v[170:171], v244 offset:41472
	v_exp_f32_e32 v160, v172
	v_exp_f32_e32 v161, v173
	v_add_f32_e32 v15, v160, v15
	v_cvt_pk_bf16_f32 v186, v160, v161
	v_add_f32_e32 v15, v161, v15
	s_waitcnt lgkmcnt(2)
	v_mfma_f32_32x32x16_bf16 v[80:95], v[176:179], v[164:167], v[80:95]
	ds_read_b64_tr_b16 v[160:161], v244 offset:38976
	ds_read_b64_tr_b16 v[162:163], v244 offset:41536
	v_exp_f32_e32 v172, v174
	v_exp_f32_e32 v173, v175
	v_add_f32_e32 v15, v172, v15
	v_cvt_pk_bf16_f32 v187, v172, v173
	v_add_f32_e32 v15, v173, v15
	s_waitcnt lgkmcnt(2)
	v_mfma_f32_32x32x16_bf16 v[64:79], v[168:171], v[10:13], v[64:79]
	ds_read_b64_tr_b16 v[164:165], v244 offset:39040
	ds_read_b64_tr_b16 v[166:167], v244 offset:41600
	v_exp_f32_e32 v144, v144
	v_max3_f32 v172, v128, s33, v80
	v_add_f32_e32 v15, v144, v15
	s_waitcnt lgkmcnt(2)
	v_mfma_f32_32x32x16_bf16 v[48:63], v[160:163], v[10:13], v[48:63]
	ds_read_b64_tr_b16 v[168:169], v244 offset:39104
	v_exp_f32_e32 v145, v145
	ds_read_b64_tr_b16 v[170:171], v244 offset:41664
	v_cvt_pk_bf16_f32 v176, v144, v145
	v_max3_f32 v144, v172, v129, v81
	v_add_f32_e32 v15, v145, v15
	s_waitcnt lgkmcnt(2)
	v_mfma_f32_32x32x16_bf16 v[32:47], v[164:167], v[10:13], v[32:47]
	ds_read_b64_tr_b16 v[160:161], v244 offset:44032
	ds_read_b64_tr_b16 v[162:163], v244 offset:46592
	v_exp_f32_e32 v145, v146
	v_max3_f32 v144, v144, v130, v82
	v_add_f32_e32 v15, v145, v15
	s_waitcnt lgkmcnt(2)
	v_mfma_f32_32x32x16_bf16 v[16:31], v[168:171], v[10:13], v[16:31]
	ds_read_b64_tr_b16 v[164:165], v244 offset:44096
	ds_read_b64_tr_b16 v[166:167], v244 offset:46656
	v_exp_f32_e32 v10, v147
	v_max3_f32 v144, v144, v131, v83
	v_cvt_pk_bf16_f32 v177, v145, v10
	v_add_f32_e32 v15, v10, v15
	s_waitcnt lgkmcnt(2)
	v_mfma_f32_32x32x16_bf16 v[64:79], v[160:163], v[6:9], v[64:79]
	ds_read_b64_tr_b16 v[10:11], v244 offset:44160
	ds_read_b64_tr_b16 v[12:13], v244 offset:46720
	v_exp_f32_e32 v148, v148
	v_max3_f32 v160, v144, v132, v84
	v_add_f32_e32 v15, v148, v15
	s_waitcnt lgkmcnt(2)
	v_mfma_f32_32x32x16_bf16 v[48:63], v[164:167], v[6:9], v[48:63]
	ds_read_b64_tr_b16 v[144:145], v244 offset:44224
	v_exp_f32_e32 v149, v149
	ds_read_b64_tr_b16 v[146:147], v244 offset:46784
	v_cvt_pk_bf16_f32 v178, v148, v149
	v_max3_f32 v148, v160, v133, v85
	v_add_f32_e32 v15, v149, v15
	s_waitcnt lgkmcnt(2)
	v_mfma_f32_32x32x16_bf16 v[32:47], v[10:13], v[6:9], v[32:47]
	ds_read_b64_tr_b16 v[160:161], v244 offset:49152
	ds_read_b64_tr_b16 v[162:163], v244 offset:51712
	v_exp_f32_e32 v149, v150
	v_max3_f32 v148, v148, v134, v86
	v_add_f32_e32 v15, v149, v15
	s_waitcnt lgkmcnt(2)
	v_mfma_f32_32x32x16_bf16 v[16:31], v[144:147], v[6:9], v[16:31]
	ds_read_b64_tr_b16 v[10:11], v244 offset:49216
	ds_read_b64_tr_b16 v[12:13], v244 offset:51776
	v_exp_f32_e32 v6, v151
	v_max3_f32 v144, v148, v135, v87
	v_cvt_pk_bf16_f32 v179, v149, v6
	v_add_f32_e32 v15, v6, v15
	s_waitcnt lgkmcnt(2)
	v_mfma_f32_32x32x16_bf16 v[64:79], v[160:163], v[2:5], v[64:79]
	ds_read_b64_tr_b16 v[6:7], v244 offset:49280
	ds_read_b64_tr_b16 v[8:9], v244 offset:51840
	v_exp_f32_e32 v148, v152
	v_max3_f32 v149, v144, v136, v88
	v_add_f32_e32 v15, v148, v15
	s_waitcnt lgkmcnt(2)
	v_mfma_f32_32x32x16_bf16 v[48:63], v[10:13], v[2:5], v[48:63]
	ds_read_b64_tr_b16 v[144:145], v244 offset:49344
	v_exp_f32_e32 v10, v153
	ds_read_b64_tr_b16 v[146:147], v244 offset:51904
	v_cvt_pk_bf16_f32 v180, v148, v10
	v_max3_f32 v148, v149, v137, v89
	v_add_f32_e32 v15, v10, v15
	s_waitcnt lgkmcnt(2)
	v_mfma_f32_32x32x16_bf16 v[32:47], v[6:9], v[2:5], v[32:47]
	ds_read_b64_tr_b16 v[10:11], v244 offset:54272
	ds_read_b64_tr_b16 v[12:13], v244 offset:56832
	v_exp_f32_e32 v149, v154
	v_max3_f32 v148, v148, v138, v90
	v_add_f32_e32 v15, v149, v15
	s_waitcnt lgkmcnt(2)
	v_mfma_f32_32x32x16_bf16 v[16:31], v[144:147], v[2:5], v[16:31]
	ds_read_b64_tr_b16 v[6:7], v244 offset:54336
	ds_read_b64_tr_b16 v[8:9], v244 offset:56896
	v_exp_f32_e32 v2, v155
	v_max3_f32 v144, v148, v139, v91
	v_cvt_pk_bf16_f32 v181, v149, v2
	v_add_f32_e32 v15, v2, v15
	s_waitcnt lgkmcnt(2)
	v_mfma_f32_32x32x16_bf16 v[64:79], v[10:13], v[192:195], v[64:79]
	ds_read_b64_tr_b16 v[2:3], v244 offset:54400
	ds_read_b64_tr_b16 v[4:5], v244 offset:56960
	v_exp_f32_e32 v145, v156
	v_max3_f32 v144, v144, v140, v92
	v_add_f32_e32 v15, v145, v15
	s_waitcnt lgkmcnt(2)
	v_mfma_f32_32x32x16_bf16 v[48:63], v[6:9], v[192:195], v[48:63]
	ds_read_b64_tr_b16 v[10:11], v244 offset:54464
	v_exp_f32_e32 v6, v157
	ds_read_b64_tr_b16 v[12:13], v244 offset:57024
	v_add_f32_e32 v7, v6, v15
	v_cvt_pk_bf16_f32 v182, v145, v6
	v_max3_f32 v6, v144, v141, v93
	s_waitcnt lgkmcnt(2)
	v_mfma_f32_32x32x16_bf16 v[32:47], v[2:5], v[192:195], v[32:47]
	v_exp_f32_e32 v3, v158
	v_max3_f32 v4, v6, v142, v94
	v_add_f32_e32 v2, v3, v7
	s_waitcnt lgkmcnt(0)
	v_mfma_f32_32x32x16_bf16 v[16:31], v[10:13], v[192:195], v[16:31]
	v_exp_f32_e32 v5, v159
	v_cmp_gt_f32_e32 vcc, 1.0, v0
	v_add_f32_e32 v2, v5, v2
	v_mov_b32_e32 v239, v2
	v_cvt_pk_bf16_f32 v183, v3, v5
	v_max3_f32 v3, v4, v143, v95
	v_permlane32_swap_b32_e32 v2, v239
	s_cbranch_vccz .LBB0_589
	v_pk_mul_f32 v[78:79], v[0:1], v[78:79] op_sel_hi:[0,1]
	v_pk_mul_f32 v[76:77], v[0:1], v[76:77] op_sel_hi:[0,1]
	v_pk_mul_f32 v[74:75], v[0:1], v[74:75] op_sel_hi:[0,1]
	v_pk_mul_f32 v[72:73], v[0:1], v[72:73] op_sel_hi:[0,1]
	v_pk_mul_f32 v[70:71], v[0:1], v[70:71] op_sel_hi:[0,1]
	v_pk_mul_f32 v[68:69], v[0:1], v[68:69] op_sel_hi:[0,1]
	v_pk_mul_f32 v[66:67], v[0:1], v[66:67] op_sel_hi:[0,1]
	v_pk_mul_f32 v[64:65], v[0:1], v[64:65] op_sel_hi:[0,1]
	v_pk_mul_f32 v[62:63], v[0:1], v[62:63] op_sel_hi:[0,1]
	v_pk_mul_f32 v[60:61], v[0:1], v[60:61] op_sel_hi:[0,1]
	v_pk_mul_f32 v[58:59], v[0:1], v[58:59] op_sel_hi:[0,1]
	v_pk_mul_f32 v[56:57], v[0:1], v[56:57] op_sel_hi:[0,1]
	v_pk_mul_f32 v[54:55], v[0:1], v[54:55] op_sel_hi:[0,1]
	v_pk_mul_f32 v[52:53], v[0:1], v[52:53] op_sel_hi:[0,1]
	v_pk_mul_f32 v[50:51], v[0:1], v[50:51] op_sel_hi:[0,1]
	v_pk_mul_f32 v[48:49], v[0:1], v[48:49] op_sel_hi:[0,1]
	v_pk_mul_f32 v[46:47], v[0:1], v[46:47] op_sel_hi:[0,1]
	v_pk_mul_f32 v[44:45], v[0:1], v[44:45] op_sel_hi:[0,1]
	v_pk_mul_f32 v[42:43], v[0:1], v[42:43] op_sel_hi:[0,1]
	v_pk_mul_f32 v[40:41], v[0:1], v[40:41] op_sel_hi:[0,1]
	v_pk_mul_f32 v[38:39], v[0:1], v[38:39] op_sel_hi:[0,1]
	v_pk_mul_f32 v[36:37], v[0:1], v[36:37] op_sel_hi:[0,1]
	v_pk_mul_f32 v[34:35], v[0:1], v[34:35] op_sel_hi:[0,1]
	v_pk_mul_f32 v[32:33], v[0:1], v[32:33] op_sel_hi:[0,1]
	v_pk_mul_f32 v[30:31], v[0:1], v[30:31] op_sel_hi:[0,1]
	v_pk_mul_f32 v[28:29], v[0:1], v[28:29] op_sel_hi:[0,1]
	v_pk_mul_f32 v[26:27], v[0:1], v[26:27] op_sel_hi:[0,1]
	v_pk_mul_f32 v[24:25], v[0:1], v[24:25] op_sel_hi:[0,1]
	v_pk_mul_f32 v[22:23], v[0:1], v[22:23] op_sel_hi:[0,1]
	v_pk_mul_f32 v[20:21], v[0:1], v[20:21] op_sel_hi:[0,1]
	v_pk_mul_f32 v[18:19], v[0:1], v[18:19] op_sel_hi:[0,1]
	v_pk_mul_f32 v[16:17], v[0:1], v[16:17] op_sel_hi:[0,1]
.LBB0_589:
	v_add_f32_e32 v0, v2, v239
	v_add_f32_e32 v222, v14, v0
	v_mov_b32_e32 v0, v3
	s_cmp_ge_u32 s13, s16
	v_mov_b32_e32 v220, 1.0
	v_permlane32_swap_b32_e32 v3, v0
	s_cbranch_scc1 .LBB0_593
	v_max_f32_e32 v2, v3, v3
	v_max_f32_e32 v0, v0, v0
	v_max_f32_e32 v0, v2, v0
	v_cmp_lt_f32_e32 vcc, s28, v0
	s_cbranch_vccz .LBB0_592
	v_max_f32_e32 v0, v0, v0
	v_max_f32_e32 v0, 0, v0
	v_exp_f32_e64 v220, -v0
	v_add_f32_e32 v221, v221, v0
	v_xor_b32_e32 v112, 0x80000000, v221
	v_sub_f32_e32 v143, v143, v0
	v_sub_f32_e32 v142, v142, v0
	v_sub_f32_e32 v141, v141, v0
	v_sub_f32_e32 v140, v140, v0
	v_sub_f32_e32 v139, v139, v0
	v_sub_f32_e32 v138, v138, v0
	v_sub_f32_e32 v137, v137, v0
	v_sub_f32_e32 v136, v136, v0
	v_sub_f32_e32 v135, v135, v0
	v_sub_f32_e32 v134, v134, v0
	v_sub_f32_e32 v133, v133, v0
	v_sub_f32_e32 v132, v132, v0
	v_sub_f32_e32 v131, v131, v0
	v_sub_f32_e32 v130, v130, v0
	v_sub_f32_e32 v129, v129, v0
	v_sub_f32_e32 v128, v128, v0
	v_sub_f32_e32 v95, v95, v0
	v_sub_f32_e32 v94, v94, v0
	v_sub_f32_e32 v93, v93, v0
	v_sub_f32_e32 v92, v92, v0
	v_sub_f32_e32 v91, v91, v0
	v_sub_f32_e32 v90, v90, v0
	v_sub_f32_e32 v89, v89, v0
	v_sub_f32_e32 v88, v88, v0
	v_sub_f32_e32 v87, v87, v0
	v_sub_f32_e32 v86, v86, v0
	v_sub_f32_e32 v85, v85, v0
	v_sub_f32_e32 v84, v84, v0
	v_sub_f32_e32 v83, v83, v0
	v_sub_f32_e32 v82, v82, v0
	v_sub_f32_e32 v81, v81, v0
	v_sub_f32_e32 v80, v80, v0
	v_mul_f32_e32 v222, v222, v220
	v_mov_b32_e32 v113, v112
	v_mov_b32_e32 v114, v112
	v_mov_b32_e32 v115, v112
	v_mov_b32_e32 v116, v112
	v_mov_b32_e32 v117, v112
	v_mov_b32_e32 v118, v112
	v_mov_b32_e32 v119, v112
	v_mov_b32_e32 v120, v112
	v_mov_b32_e32 v121, v112
	v_mov_b32_e32 v122, v112
	v_mov_b32_e32 v123, v112
	v_mov_b32_e32 v124, v112
	v_mov_b32_e32 v125, v112
	v_mov_b32_e32 v126, v112
	v_mov_b32_e32 v127, v112
	v_mov_b32_e32 v111, v112
	v_mov_b32_e32 v110, v112
	v_mov_b32_e32 v109, v112
	v_mov_b32_e32 v108, v112
	v_mov_b32_e32 v107, v112
	v_mov_b32_e32 v106, v112
	v_mov_b32_e32 v105, v112
	v_mov_b32_e32 v104, v112
	v_mov_b32_e32 v103, v112
	v_mov_b32_e32 v102, v112
	v_mov_b32_e32 v101, v112
	v_mov_b32_e32 v100, v112
	v_mov_b32_e32 v99, v112
	v_mov_b32_e32 v98, v112
	v_mov_b32_e32 v97, v112
	v_mov_b32_e32 v96, v112
	s_branch .LBB0_593
